# latent scan chunk loop: ten default next-chunk register copies moved to the last-chunk path only, on v38
# speedup vs baseline: 1.0048x; 1.0020x over previous
.LBB0_483:
	s_or_b64 exec, exec, s[36:37]
	ds_read_b128 v[136:139], v193
	ds_read_b128 v[124:127], v193 offset:16
	ds_read_b128 v[132:135], v193 offset:768
	ds_read_b128 v[120:123], v193 offset:784
	ds_read_b128 v[100:103], v193 offset:256
	ds_read_b128 v[92:95], v193 offset:272
	ds_read_b128 v[144:147], v193 offset:512
	ds_read_b128 v[128:131], v193 offset:528
	ds_read_b128 v[140:143], v193 offset:1024
	ds_read_b128 v[116:119], v193 offset:1040
	s_add_i32 s2, s15, 1
	s_cmp_gt_u32 s15, 62
	s_cbranch_scc1 .Lch_last
	v_lshl_add_u32 v50, s2, 5, v192
	v_sub_u32_e32 v48, 0x7ff, v50
	v_cndmask_b32_e64 v48, v48, v50, s[8:9]
	v_ashrrev_i32_e32 v49, 31, v48
	v_lshl_add_u64 v[48:49], v[48:49], 0, s[20:21]
	v_cmp_lt_i32_e32 vcc, 0, v50
	v_mov_b64_e32 v[60:61], v[48:49]
	s_and_saveexec_b64 s[16:17], vcc
	s_cbranch_execz .LBB0_489
	s_and_b64 vcc, exec, s[10:11]
	s_mov_b64 s[36:37], -1
	s_cbranch_vccnz .LBB0_487
	v_lshl_add_u64 v[60:61], v[48:49], 0, 1
	s_mov_b64 s[36:37], 0

.Lch_last:
	v_mov_b64_e32 v[84:85], v[104:105]
	v_mov_b64_e32 v[68:69], v[88:89]
	v_mov_b64_e32 v[72:73], v[96:97]
	v_mov_b64_e32 v[76:77], v[108:109]
	v_mov_b64_e32 v[80:81], v[112:113]
	v_mov_b64_e32 v[86:87], v[106:107]
	v_mov_b64_e32 v[70:71], v[90:91]
	v_mov_b64_e32 v[74:75], v[98:99]
	v_mov_b64_e32 v[78:79], v[110:111]
	v_mov_b64_e32 v[82:83], v[114:115]
	s_branch .LBB0_490
